# first RMSNorm row loop unrolled by three with renamed row-register sets and a counted vmcnt (rows r+1, r+2 stay in flight)
# baseline (speedup 1.0000x reference)
; DI void phase_ln(const Params& p, int layer, int sub, bool first, bool final_, const u16* M, int glayer, int goff) {
;     ...
;   auto load_row = [&](int row, float4 (&v)[4], u32x2 (&mm)[4]) {
;     const float* xr = first ? xin_row(p, row) : (p.out + (size_t)row * DM);
; #pragma unroll
;     for (int j = 0; j < 4; ++j) {
;       const f32x4v t_ = __builtin_nontemporal_load((const f32x4v*)(xr + j * 256 + lane * 4));
;       v[j] = (float4){t_.x, t_.y, t_.z, t_.w};
;     ...
;   for (int row = r0; row < r1; ++row) {
;     if (row + 2 < r1) load_row(row + 2, vn2, mmn2);
;     int bb, tokbase, S;
;     seq_of_token(row, bb, tokbase, S);
;     if (bb != cur_bb) {
;       cur_bb = bb;
;       const float* mrow = mod + (layer * 10 + bb) * 6144 + sub * 3072;
;       const float* grow = mod + (glayer * 10 + bb) * 6144 + goff;
; #pragma unroll
;       for (int j = 0; j < 4; ++j) {
;         const int c = j * 256 + lane * 4;
;         const float4 g = *(const float4*)(gn + c);
;         if (final_) { pg[j] = g; psh[j] = (float4){0.f, 0.f, 0.f, 0.f}; }
;         else {
;           const float4 sh = *(const float4*)(mrow + c);
;           const float4 sc = *(const float4*)(mrow + 1024 + c);
;           pg[j] = (float4){g.x * (1.f + sc.x), g.y * (1.f + sc.y), g.z * (1.f + sc.z), g.w * (1.f + sc.w)};
;           psh[j] = sh;
;         }
;         if (M) pgm[j] = *(const float4*)(grow + c);
;       }
;     }
.Lln1_0_h:
	v_add_u32_e32 v67, 2, v66
	v_add_u32_e32 v75, -1, v94
	v_min_i32_e32 v67, v67, v75
	v_add_u32_e32 v102, 0xffff8000, v67
	v_cmp_gt_i32_e32 vcc, s48, v67
	v_mov_b32_e32 v103, 0
	v_mov_b32_e32 v104, s18
	v_mov_b32_e32 v75, s16
	v_mov_b32_e32 v105, s19
	v_mov_b32_e32 v106, s17
	v_cndmask_b32_e32 v102, v102, v67, vcc
	v_cndmask_b32_e32 v104, v104, v75, vcc
	v_cndmask_b32_e32 v105, v105, v106, vcc
	v_lshlrev_b64 v[102:103], 12, v[102:103]
	v_lshl_add_u64 v[102:103], v[104:105], 0, v[102:103]
	v_lshl_add_u64 v[102:103], v[102:103], 0, v[0:1]
	global_load_dwordx4 v[6:9], v[102:103], off nt
	global_load_dwordx4 v[46:49], v[102:103], off offset:1024 nt
	global_load_dwordx4 v[54:57], v[102:103], off offset:2048 nt
	global_load_dwordx4 v[58:61], v[102:103], off offset:3072 nt
.Lln1_0_k:
	v_add_u32_e32 v75, 0xffff8000, v66
	v_lshrrev_b32_e32 v75, 11, v75
	v_ashrrev_i32_e32 v67, 14, v66
	v_add_u32_e32 v75, 2, v75
	v_cmp_gt_i32_e32 vcc, s48, v66
	s_nop 1
	v_cndmask_b32_e32 v67, v75, v67, vcc
	v_cmp_ne_u32_e32 vcc, v67, v73
	s_and_saveexec_b64 s[10:11], vcc
	s_cbranch_execz .Lln1_0_c
	v_mul_i32_i24_e32 v38, 0x1800, v67
	v_ashrrev_i32_e32 v39, 31, v38
	v_lshl_add_u64 v[38:39], v[38:39], 2, s[88:89]
	v_lshl_add_u64 v[90:91], v[38:39], 0, s[44:45]
	v_lshl_add_u64 v[92:93], v[38:39], 0, v[0:1]
	v_lshl_add_u64 v[50:51], v[90:91], 0, v[0:1]
	global_load_dwordx4 v[38:41], v[92:93], off
	global_load_dwordx4 v[42:45], v[68:69], off
	s_nop 0
	global_load_dwordx4 v[50:53], v[50:51], off
	v_mov_b32_e32 v73, v1
	v_lshl_add_u64 v[62:63], v[90:91], 0, v[72:73]
	v_mov_b32_e32 v75, v1
	v_lshl_add_u64 v[86:87], v[90:91], 0, v[74:75]
	v_mov_b32_e32 v77, v1
	v_lshl_add_u64 v[102:103], v[90:91], 0, v[76:77]
	v_mov_b32_e32 v73, v67
	s_waitcnt vmcnt(0)
	v_pk_add_f32 v[50:51], v[50:51], 1.0 op_sel_hi:[1,0]
	s_nop 0
	v_pk_mul_f32 v[78:79], v[42:43], v[50:51]
	v_pk_add_f32 v[42:43], v[52:53], 1.0 op_sel_hi:[1,0]
	s_nop 0
	v_pk_mul_f32 v[80:81], v[44:45], v[42:43]
	global_load_dwordx4 v[42:45], v[92:93], off offset:1024
	global_load_dwordx4 v[50:53], v[68:69], off offset:1024
	s_nop 0
	global_load_dwordx4 v[62:65], v[62:63], off
	s_waitcnt vmcnt(0)
	v_pk_add_f32 v[62:63], v[62:63], 1.0 op_sel_hi:[1,0]
	s_nop 0
	v_pk_mul_f32 v[82:83], v[50:51], v[62:63]
	v_pk_add_f32 v[50:51], v[64:65], 1.0 op_sel_hi:[1,0]
	s_nop 0
	v_pk_mul_f32 v[84:85], v[52:53], v[50:51]
	global_load_dwordx4 v[50:53], v[92:93], off offset:2048
	global_load_dwordx4 v[62:65], v[68:69], off offset:2048
	s_nop 0
	global_load_dwordx4 v[86:89], v[86:87], off
	s_waitcnt vmcnt(0)
	v_pk_add_f32 v[86:87], v[86:87], 1.0 op_sel_hi:[1,0]
	s_nop 0
	v_pk_mul_f32 v[86:87], v[62:63], v[86:87]
	v_pk_add_f32 v[62:63], v[88:89], 1.0 op_sel_hi:[1,0]
	s_nop 0
	v_pk_mul_f32 v[88:89], v[64:65], v[62:63]
	global_load_dwordx4 v[62:65], v[92:93], off offset:3072
	s_nop 0
	global_load_dwordx4 v[90:93], v[68:69], off offset:3072
	s_nop 0
	global_load_dwordx4 v[102:105], v[102:103], off
	s_waitcnt vmcnt(0)
	v_pk_add_f32 v[102:103], v[102:103], 1.0 op_sel_hi:[1,0]
	s_nop 0
	v_pk_mul_f32 v[90:91], v[90:91], v[102:103]
	v_pk_add_f32 v[102:103], v[104:105], 1.0 op_sel_hi:[1,0]
	s_nop 0
	v_pk_mul_f32 v[92:93], v[92:93], v[102:103]
	s_branch .Lln1_0_c
; DI void phase_ln(const Params& p, int layer, int sub, bool first, bool final_, const u16* M, int glayer, int goff) {
;     ...
;   auto load_row = [&](int row, float4 (&v)[4], u32x2 (&mm)[4]) {
;     const float* xr = first ? xin_row(p, row) : (p.out + (size_t)row * DM);
; #pragma unroll
;     for (int j = 0; j < 4; ++j) {
;       const f32x4v t_ = __builtin_nontemporal_load((const f32x4v*)(xr + j * 256 + lane * 4));
;       v[j] = (float4){t_.x, t_.y, t_.z, t_.w};
;     ...
;     float ss = 0.f;
; #pragma unroll
;     for (int j = 0; j < 4; ++j) ss += v[j].x * v[j].x + v[j].y * v[j].y + v[j].z * v[j].z + v[j].w * v[j].w;
; #pragma unroll
;     for (int o = 1; o < 64; o <<= 1) ss += __shfl_xor(ss, o);
;     const float rstd = rsqrtf(ss * (1.f / 1024.f) + 1e-6f);
;     if (final_) {
; #pragma unroll
;       for (int j = 0; j < 4; ++j) {
;         float4 o4 = {v[j].x * rstd * pg[j].x, v[j].y * rstd * pg[j].y, v[j].z * rstd * pg[j].z, v[j].w * rstd * pg[j].w};
;         const f32x4v t_ = {o4.x, o4.y, o4.z, o4.w};
;         __builtin_nontemporal_store(t_, (f32x4v*)(p.out + (size_t)row * DM + j * 256 + lane * 4));
;       }
;     } else {
; #pragma unroll
;       for (int j = 0; j < 4; ++j) {
;         const int c = j * 256 + lane * 4;
;         const float a0 = v[j].x * rstd * pg[j].x + psh[j].x;
;         const float a1 = v[j].y * rstd * pg[j].y + psh[j].y;
;         const float a2 = v[j].z * rstd * pg[j].z + psh[j].z;
;         const float a3 = v[j].w * rstd * pg[j].w + psh[j].w;
;         u32x2 o2 = {pk_bf16(a0, a1), pk_bf16(a2, a3)};
;         *(u32x2*)(H + (size_t)row * DM + c) = o2;
;       }
.Lln1_0_c:
	s_or_b64 exec, exec, s[10:11]
	s_waitcnt vmcnt(16)
	v_mov_b32_e32 v102, v34
	v_mov_b32_e32 v103, v26
	v_pk_mul_f32 v[102:103], v[102:103], v[102:103]
	v_mov_b32_e32 v104, v35
	v_mov_b32_e32 v105, v27
	v_pk_fma_f32 v[102:103], v[104:105], v[104:105], v[102:103]
	v_mov_b32_e32 v104, v36
	v_mov_b32_e32 v105, v28
	v_pk_fma_f32 v[102:103], v[104:105], v[104:105], v[102:103]
	v_mov_b32_e32 v104, v37
	v_mov_b32_e32 v105, v29
	v_pk_fma_f32 v[102:103], v[104:105], v[104:105], v[102:103]
	v_mov_b32_e32 v104, v30
	v_mov_b32_e32 v105, v22
	v_pk_mul_f32 v[104:105], v[104:105], v[104:105]
	v_mov_b32_e32 v106, v31
	v_mov_b32_e32 v107, v23
	v_pk_fma_f32 v[104:105], v[106:107], v[106:107], v[104:105]
	v_mov_b32_e32 v106, v32
	v_mov_b32_e32 v107, v24
	v_pk_fma_f32 v[104:105], v[106:107], v[106:107], v[104:105]
	v_mov_b32_e32 v106, v33
	v_mov_b32_e32 v107, v25
	v_pk_fma_f32 v[104:105], v[106:107], v[106:107], v[104:105]
	v_add_f32_e32 v67, v102, v103
	v_add_f32_e32 v67, v105, v67
	v_add_f32_e32 v67, v104, v67
	ds_bpermute_b32 v75, v95, v67
	v_add_u32_e32 v66, 1, v66
	s_waitcnt lgkmcnt(0)
	v_add_f32_e32 v67, v67, v75
	ds_bpermute_b32 v75, v96, v67
	s_waitcnt lgkmcnt(0)
	v_add_f32_e32 v67, v67, v75
	ds_bpermute_b32 v75, v97, v67
	s_waitcnt lgkmcnt(0)
	v_add_f32_e32 v67, v67, v75
	ds_bpermute_b32 v75, v98, v67
	s_waitcnt lgkmcnt(0)
	v_add_f32_e32 v67, v67, v75
	ds_bpermute_b32 v75, v99, v67
	s_waitcnt lgkmcnt(0)
	v_add_f32_e32 v67, v67, v75
	ds_bpermute_b32 v75, v100, v67
	s_waitcnt lgkmcnt(0)
	v_add_f32_e32 v67, v67, v75
	v_fmamk_f32 v67, v67, 0x3a800000, v205
	v_mul_f32_e32 v75, 0x4b800000, v67
	v_cmp_gt_f32_e32 vcc, s49, v67
	s_nop 1
	v_cndmask_b32_e32 v67, v67, v75, vcc
	v_rsq_f32_e32 v67, v67
	s_nop 0
	v_mul_f32_e32 v75, 0x45800000, v67
	v_cndmask_b32_e32 v102, v67, v75, vcc
	v_pk_mul_f32 v[22:23], v[22:23], v[102:103] op_sel_hi:[1,0]
	v_pk_mul_f32 v[24:25], v[24:25], v[102:103] op_sel_hi:[1,0]
	v_pk_fma_f32 v[22:23], v[86:87], v[22:23], v[50:51]
	v_pk_fma_f32 v[24:25], v[88:89], v[24:25], v[52:53]
	v_pk_mul_f32 v[26:27], v[26:27], v[102:103] op_sel_hi:[1,0]
	v_pk_mul_f32 v[28:29], v[28:29], v[102:103] op_sel_hi:[1,0]
	v_cvt_pk_bf16_f32 v22, v22, v23
	v_cvt_pk_bf16_f32 v23, v24, v25
	v_pk_mul_f32 v[34:35], v[34:35], v[102:103] op_sel_hi:[1,0]
	v_pk_mul_f32 v[36:37], v[36:37], v[102:103] op_sel_hi:[1,0]
	v_pk_fma_f32 v[26:27], v[78:79], v[26:27], v[38:39]
	v_pk_fma_f32 v[28:29], v[80:81], v[28:29], v[40:41]
	global_store_dwordx2 v[70:71], v[22:23], off offset:1024
	v_pk_mul_f32 v[22:23], v[30:31], v[102:103] op_sel_hi:[1,0]
	v_pk_mul_f32 v[24:25], v[32:33], v[102:103] op_sel_hi:[1,0]
	v_pk_fma_f32 v[34:35], v[82:83], v[34:35], v[42:43]
	v_pk_fma_f32 v[36:37], v[84:85], v[36:37], v[44:45]
	v_cvt_pk_bf16_f32 v26, v26, v27
	v_cvt_pk_bf16_f32 v27, v28, v29
	v_pk_fma_f32 v[22:23], v[90:91], v[22:23], v[62:63]
	v_pk_fma_f32 v[24:25], v[92:93], v[24:25], v[64:65]
	global_store_dwordx2 v[70:71], v[26:27], off
	v_cvt_pk_bf16_f32 v26, v34, v35
	v_cvt_pk_bf16_f32 v27, v36, v37
	v_cvt_pk_bf16_f32 v22, v22, v23
	v_cvt_pk_bf16_f32 v23, v24, v25
	v_cmp_ge_i32_e32 vcc, v66, v94
	global_store_dwordx2 v[70:71], v[26:27], off offset:512
	global_store_dwordx2 v[70:71], v[22:23], off offset:1536
	v_lshl_add_u64 v[70:71], v[70:71], 0, s[54:55]
	s_or_b64 s[8:9], vcc, s[8:9]
	s_andn2_b64 exec, exec, s[8:9]
	s_cbranch_execz .LBB0_400
.Lln1_1_h:
	v_add_u32_e32 v67, 2, v66
	v_add_u32_e32 v75, -1, v94
	v_min_i32_e32 v67, v67, v75
	v_add_u32_e32 v102, 0xffff8000, v67
	v_cmp_gt_i32_e32 vcc, s48, v67
	v_mov_b32_e32 v103, 0
	v_mov_b32_e32 v104, s18
	v_mov_b32_e32 v75, s16
	v_mov_b32_e32 v105, s19
	v_mov_b32_e32 v106, s17
	v_cndmask_b32_e32 v102, v102, v67, vcc
	v_cndmask_b32_e32 v104, v104, v75, vcc
	v_cndmask_b32_e32 v105, v105, v106, vcc
	v_lshlrev_b64 v[102:103], 12, v[102:103]
	v_lshl_add_u64 v[102:103], v[104:105], 0, v[102:103]
	v_lshl_add_u64 v[102:103], v[102:103], 0, v[0:1]
	global_load_dwordx4 v[26:29], v[102:103], off nt
	global_load_dwordx4 v[34:37], v[102:103], off offset:1024 nt
	global_load_dwordx4 v[22:25], v[102:103], off offset:2048 nt
	global_load_dwordx4 v[30:33], v[102:103], off offset:3072 nt

; DI void phase_ln(const Params& p, int layer, int sub, bool first, bool final_, const u16* M, int glayer, int goff) {
;     ...
;   auto load_row = [&](int row, float4 (&v)[4], u32x2 (&mm)[4]) {
;     const float* xr = first ? xin_row(p, row) : (p.out + (size_t)row * DM);
; #pragma unroll
;     for (int j = 0; j < 4; ++j) {
;       const f32x4v t_ = __builtin_nontemporal_load((const f32x4v*)(xr + j * 256 + lane * 4));
;       v[j] = (float4){t_.x, t_.y, t_.z, t_.w};
;     ...
;     float ss = 0.f;
; #pragma unroll
;     for (int j = 0; j < 4; ++j) ss += v[j].x * v[j].x + v[j].y * v[j].y + v[j].z * v[j].z + v[j].w * v[j].w;
; #pragma unroll
;     for (int o = 1; o < 64; o <<= 1) ss += __shfl_xor(ss, o);
;     const float rstd = rsqrtf(ss * (1.f / 1024.f) + 1e-6f);
;     if (final_) {
; #pragma unroll
;       for (int j = 0; j < 4; ++j) {
;         float4 o4 = {v[j].x * rstd * pg[j].x, v[j].y * rstd * pg[j].y, v[j].z * rstd * pg[j].z, v[j].w * rstd * pg[j].w};
;         const f32x4v t_ = {o4.x, o4.y, o4.z, o4.w};
;         __builtin_nontemporal_store(t_, (f32x4v*)(p.out + (size_t)row * DM + j * 256 + lane * 4));
;       }
;     } else {
; #pragma unroll
;       for (int j = 0; j < 4; ++j) {
;         const int c = j * 256 + lane * 4;
;         const float a0 = v[j].x * rstd * pg[j].x + psh[j].x;
;         const float a1 = v[j].y * rstd * pg[j].y + psh[j].y;
;         const float a2 = v[j].z * rstd * pg[j].z + psh[j].z;
;         const float a3 = v[j].w * rstd * pg[j].w + psh[j].w;
;         u32x2 o2 = {pk_bf16(a0, a1), pk_bf16(a2, a3)};
;         *(u32x2*)(H + (size_t)row * DM + c) = o2;
;       }
.Lln1_1_c:
	s_or_b64 exec, exec, s[10:11]
	s_waitcnt vmcnt(16)
	v_mov_b32_e32 v102, v10
	v_mov_b32_e32 v103, v2
	v_pk_mul_f32 v[102:103], v[102:103], v[102:103]
	v_mov_b32_e32 v104, v11
	v_mov_b32_e32 v105, v3
	v_pk_fma_f32 v[102:103], v[104:105], v[104:105], v[102:103]
	v_mov_b32_e32 v104, v12
	v_mov_b32_e32 v105, v4
	v_pk_fma_f32 v[102:103], v[104:105], v[104:105], v[102:103]
	v_mov_b32_e32 v104, v13
	v_mov_b32_e32 v105, v5
	v_pk_fma_f32 v[102:103], v[104:105], v[104:105], v[102:103]
	v_mov_b32_e32 v104, v18
	v_mov_b32_e32 v105, v14
	v_pk_mul_f32 v[104:105], v[104:105], v[104:105]
	v_mov_b32_e32 v106, v19
	v_mov_b32_e32 v107, v15
	v_pk_fma_f32 v[104:105], v[106:107], v[106:107], v[104:105]
	v_mov_b32_e32 v106, v20
	v_mov_b32_e32 v107, v16
	v_pk_fma_f32 v[104:105], v[106:107], v[106:107], v[104:105]
	v_mov_b32_e32 v106, v21
	v_mov_b32_e32 v107, v17
	v_pk_fma_f32 v[104:105], v[106:107], v[106:107], v[104:105]
	v_add_f32_e32 v67, v102, v103
	v_add_f32_e32 v67, v105, v67
	v_add_f32_e32 v67, v104, v67
	ds_bpermute_b32 v75, v95, v67
	v_add_u32_e32 v66, 1, v66
	s_waitcnt lgkmcnt(0)
	v_add_f32_e32 v67, v67, v75
	ds_bpermute_b32 v75, v96, v67
	s_waitcnt lgkmcnt(0)
	v_add_f32_e32 v67, v67, v75
	ds_bpermute_b32 v75, v97, v67
	s_waitcnt lgkmcnt(0)
	v_add_f32_e32 v67, v67, v75
	ds_bpermute_b32 v75, v98, v67
	s_waitcnt lgkmcnt(0)
	v_add_f32_e32 v67, v67, v75
	ds_bpermute_b32 v75, v99, v67
	s_waitcnt lgkmcnt(0)
	v_add_f32_e32 v67, v67, v75
	ds_bpermute_b32 v75, v100, v67
	s_waitcnt lgkmcnt(0)
	v_add_f32_e32 v67, v67, v75
	v_fmamk_f32 v67, v67, 0x3a800000, v205
	v_mul_f32_e32 v75, 0x4b800000, v67
	v_cmp_gt_f32_e32 vcc, s49, v67
	s_nop 1
	v_cndmask_b32_e32 v67, v67, v75, vcc
	v_rsq_f32_e32 v67, v67
	s_nop 0
	v_mul_f32_e32 v75, 0x45800000, v67
	v_cndmask_b32_e32 v102, v67, v75, vcc
	v_pk_mul_f32 v[14:15], v[14:15], v[102:103] op_sel_hi:[1,0]
	v_pk_mul_f32 v[16:17], v[16:17], v[102:103] op_sel_hi:[1,0]
	v_pk_fma_f32 v[14:15], v[86:87], v[14:15], v[50:51]
	v_pk_fma_f32 v[16:17], v[88:89], v[16:17], v[52:53]
	v_pk_mul_f32 v[2:3], v[2:3], v[102:103] op_sel_hi:[1,0]
	v_pk_mul_f32 v[4:5], v[4:5], v[102:103] op_sel_hi:[1,0]
	v_cvt_pk_bf16_f32 v14, v14, v15
	v_cvt_pk_bf16_f32 v15, v16, v17
	v_pk_mul_f32 v[10:11], v[10:11], v[102:103] op_sel_hi:[1,0]
	v_pk_mul_f32 v[12:13], v[12:13], v[102:103] op_sel_hi:[1,0]
	v_pk_fma_f32 v[2:3], v[78:79], v[2:3], v[38:39]
	v_pk_fma_f32 v[4:5], v[80:81], v[4:5], v[40:41]
	global_store_dwordx2 v[70:71], v[14:15], off offset:1024
	v_pk_mul_f32 v[14:15], v[18:19], v[102:103] op_sel_hi:[1,0]
	v_pk_mul_f32 v[16:17], v[20:21], v[102:103] op_sel_hi:[1,0]
	v_pk_fma_f32 v[10:11], v[82:83], v[10:11], v[42:43]
	v_pk_fma_f32 v[12:13], v[84:85], v[12:13], v[44:45]
	v_cvt_pk_bf16_f32 v2, v2, v3
	v_cvt_pk_bf16_f32 v3, v4, v5
	v_pk_fma_f32 v[14:15], v[90:91], v[14:15], v[62:63]
	v_pk_fma_f32 v[16:17], v[92:93], v[16:17], v[64:65]
	global_store_dwordx2 v[70:71], v[2:3], off
	v_cvt_pk_bf16_f32 v2, v10, v11
	v_cvt_pk_bf16_f32 v3, v12, v13
	v_cvt_pk_bf16_f32 v14, v14, v15
	v_cvt_pk_bf16_f32 v15, v16, v17
	v_cmp_ge_i32_e32 vcc, v66, v94
	global_store_dwordx2 v[70:71], v[2:3], off offset:512
	global_store_dwordx2 v[70:71], v[14:15], off offset:1536
	v_lshl_add_u64 v[70:71], v[70:71], 0, s[54:55]
	s_or_b64 s[8:9], vcc, s[8:9]
	s_andn2_b64 exec, exec, s[8:9]
	s_cbranch_execz .LBB0_400
.Lln1_2_h:
	v_add_u32_e32 v67, 2, v66
	v_add_u32_e32 v75, -1, v94
	v_min_i32_e32 v67, v67, v75
	v_add_u32_e32 v102, 0xffff8000, v67
	v_cmp_gt_i32_e32 vcc, s48, v67
	v_mov_b32_e32 v103, 0
	v_mov_b32_e32 v104, s18
	v_mov_b32_e32 v75, s16
	v_mov_b32_e32 v105, s19
	v_mov_b32_e32 v106, s17
	v_cndmask_b32_e32 v102, v102, v67, vcc
	v_cndmask_b32_e32 v104, v104, v75, vcc
	v_cndmask_b32_e32 v105, v105, v106, vcc
	v_lshlrev_b64 v[102:103], 12, v[102:103]
	v_lshl_add_u64 v[102:103], v[104:105], 0, v[102:103]
	v_lshl_add_u64 v[102:103], v[102:103], 0, v[0:1]
	global_load_dwordx4 v[2:5], v[102:103], off nt
	global_load_dwordx4 v[10:13], v[102:103], off offset:1024 nt
	global_load_dwordx4 v[14:17], v[102:103], off offset:2048 nt
	global_load_dwordx4 v[18:21], v[102:103], off offset:3072 nt

; DI void phase_ln(const Params& p, int layer, int sub, bool first, bool final_, const u16* M, int glayer, int goff) {
;     ...
;     float ss = 0.f;
; #pragma unroll
;     for (int j = 0; j < 4; ++j) ss += v[j].x * v[j].x + v[j].y * v[j].y + v[j].z * v[j].z + v[j].w * v[j].w;
; #pragma unroll
;     for (int o = 1; o < 64; o <<= 1) ss += __shfl_xor(ss, o);
;     const float rstd = rsqrtf(ss * (1.f / 1024.f) + 1e-6f);
;     if (final_) {
; #pragma unroll
;       for (int j = 0; j < 4; ++j) {
;         float4 o4 = {v[j].x * rstd * pg[j].x, v[j].y * rstd * pg[j].y, v[j].z * rstd * pg[j].z, v[j].w * rstd * pg[j].w};
;         const f32x4v t_ = {o4.x, o4.y, o4.z, o4.w};
;         __builtin_nontemporal_store(t_, (f32x4v*)(p.out + (size_t)row * DM + j * 256 + lane * 4));
;       }
;     } else {
; #pragma unroll
;       for (int j = 0; j < 4; ++j) {
;         const int c = j * 256 + lane * 4;
;         const float a0 = v[j].x * rstd * pg[j].x + psh[j].x;
;         const float a1 = v[j].y * rstd * pg[j].y + psh[j].y;
;         const float a2 = v[j].z * rstd * pg[j].z + psh[j].z;
;         const float a3 = v[j].w * rstd * pg[j].w + psh[j].w;
;         u32x2 o2 = {pk_bf16(a0, a1), pk_bf16(a2, a3)};
;         *(u32x2*)(H + (size_t)row * DM + c) = o2;
;       }
.Lln1_2_c:
	s_or_b64 exec, exec, s[10:11]
	s_waitcnt vmcnt(16)
	v_mov_b32_e32 v102, v46
	v_mov_b32_e32 v103, v6
	v_pk_mul_f32 v[102:103], v[102:103], v[102:103]
	v_mov_b32_e32 v104, v47
	v_mov_b32_e32 v105, v7
	v_pk_fma_f32 v[102:103], v[104:105], v[104:105], v[102:103]
	v_mov_b32_e32 v104, v48
	v_mov_b32_e32 v105, v8
	v_pk_fma_f32 v[102:103], v[104:105], v[104:105], v[102:103]
	v_mov_b32_e32 v104, v49
	v_mov_b32_e32 v105, v9
	v_pk_fma_f32 v[102:103], v[104:105], v[104:105], v[102:103]
	v_mov_b32_e32 v104, v58
	v_mov_b32_e32 v105, v54
	v_pk_mul_f32 v[104:105], v[104:105], v[104:105]
	v_mov_b32_e32 v106, v59
	v_mov_b32_e32 v107, v55
	v_pk_fma_f32 v[104:105], v[106:107], v[106:107], v[104:105]
	v_mov_b32_e32 v106, v60
	v_mov_b32_e32 v107, v56
	v_pk_fma_f32 v[104:105], v[106:107], v[106:107], v[104:105]
	v_mov_b32_e32 v106, v61
	v_mov_b32_e32 v107, v57
	v_pk_fma_f32 v[104:105], v[106:107], v[106:107], v[104:105]
	v_add_f32_e32 v67, v102, v103
	v_add_f32_e32 v67, v105, v67
	v_add_f32_e32 v67, v104, v67
	ds_bpermute_b32 v75, v95, v67
	v_add_u32_e32 v66, 1, v66
	s_waitcnt lgkmcnt(0)
	v_add_f32_e32 v67, v67, v75
	ds_bpermute_b32 v75, v96, v67
	s_waitcnt lgkmcnt(0)
	v_add_f32_e32 v67, v67, v75
	ds_bpermute_b32 v75, v97, v67
	s_waitcnt lgkmcnt(0)
	v_add_f32_e32 v67, v67, v75
	ds_bpermute_b32 v75, v98, v67
	s_waitcnt lgkmcnt(0)
	v_add_f32_e32 v67, v67, v75
	ds_bpermute_b32 v75, v99, v67
	s_waitcnt lgkmcnt(0)
	v_add_f32_e32 v67, v67, v75
	ds_bpermute_b32 v75, v100, v67
	s_waitcnt lgkmcnt(0)
	v_add_f32_e32 v67, v67, v75
	v_fmamk_f32 v67, v67, 0x3a800000, v205
	v_mul_f32_e32 v75, 0x4b800000, v67
	v_cmp_gt_f32_e32 vcc, s49, v67
	s_nop 1
	v_cndmask_b32_e32 v67, v67, v75, vcc
	v_rsq_f32_e32 v67, v67
	s_nop 0
	v_mul_f32_e32 v75, 0x45800000, v67
	v_cndmask_b32_e32 v102, v67, v75, vcc
	v_pk_mul_f32 v[54:55], v[54:55], v[102:103] op_sel_hi:[1,0]
	v_pk_mul_f32 v[56:57], v[56:57], v[102:103] op_sel_hi:[1,0]
	v_pk_fma_f32 v[54:55], v[86:87], v[54:55], v[50:51]
	v_pk_fma_f32 v[56:57], v[88:89], v[56:57], v[52:53]
	v_pk_mul_f32 v[6:7], v[6:7], v[102:103] op_sel_hi:[1,0]
	v_pk_mul_f32 v[8:9], v[8:9], v[102:103] op_sel_hi:[1,0]
	v_cvt_pk_bf16_f32 v54, v54, v55
	v_cvt_pk_bf16_f32 v55, v56, v57
	v_pk_mul_f32 v[46:47], v[46:47], v[102:103] op_sel_hi:[1,0]
	v_pk_mul_f32 v[48:49], v[48:49], v[102:103] op_sel_hi:[1,0]
	v_pk_fma_f32 v[6:7], v[78:79], v[6:7], v[38:39]
	v_pk_fma_f32 v[8:9], v[80:81], v[8:9], v[40:41]
	global_store_dwordx2 v[70:71], v[54:55], off offset:1024
	v_pk_mul_f32 v[54:55], v[58:59], v[102:103] op_sel_hi:[1,0]
	v_pk_mul_f32 v[56:57], v[60:61], v[102:103] op_sel_hi:[1,0]
	v_pk_fma_f32 v[46:47], v[82:83], v[46:47], v[42:43]
	v_pk_fma_f32 v[48:49], v[84:85], v[48:49], v[44:45]
	v_cvt_pk_bf16_f32 v6, v6, v7
	v_cvt_pk_bf16_f32 v7, v8, v9
	v_pk_fma_f32 v[54:55], v[90:91], v[54:55], v[62:63]
	v_pk_fma_f32 v[56:57], v[92:93], v[56:57], v[64:65]
	global_store_dwordx2 v[70:71], v[6:7], off
	v_cvt_pk_bf16_f32 v6, v46, v47
	v_cvt_pk_bf16_f32 v7, v48, v49
	v_cvt_pk_bf16_f32 v54, v54, v55
	v_cvt_pk_bf16_f32 v55, v56, v57
	v_cmp_ge_i32_e32 vcc, v66, v94
	global_store_dwordx2 v[70:71], v[6:7], off offset:512
	global_store_dwordx2 v[70:71], v[54:55], off offset:1536
	v_lshl_add_u64 v[70:71], v[70:71], 0, s[54:55]
	s_or_b64 s[8:9], vcc, s[8:9]
	s_andn2_b64 exec, exec, s[8:9]
	s_cbranch_execz .LBB0_400
	s_branch .Lln1_0_h
